# half-tile FFN-down: also skip the LDS fragment reads of the unused row half
# speedup vs baseline: 1.0031x; 1.0031x over previous
.LBB0_1247:
	s_add_u32 s16, s14, 0x100
	s_addc_u32 s17, s15, 0
	s_add_i32 s44, 0, 0x10000
	v_add_u32_e32 v110, s44, v160
	ds_read_b128 v[98:101], v110
	ds_read_b128 v[102:105], v110 offset:1024
	ds_read_b128 v[106:109], v110 offset:2048
	ds_read_b128 v[110:113], v110 offset:3072
	s_cmp_eq_u32 s43, 40
	s_cselect_b32 s21, s7, s17
	s_cselect_b32 s20, s6, s16
	s_cselect_b32 s19, s9, s42
	s_cselect_b32 s18, s8, s41
	v_lshl_add_u64 v[172:173], s[14:15], 0, v[150:151]
	s_add_i32 m0, s25, 0xc000
	ds_read_b128 v[152:155], v161
	ds_read_b128 v[156:159], v161 offset:1024
	ds_read_b128 v[176:179], v161 offset:2048
	ds_read_b128 v[180:183], v161 offset:3072
	ds_read_b128 v[184:187], v161 offset:4096
	ds_read_b128 v[188:191], v161 offset:5120
	ds_read_b128 v[192:195], v161 offset:6144
	ds_read_b128 v[196:199], v161 offset:7168
	global_load_lds_dwordx4 v[172:173], off
	v_lshl_add_u64 v[172:173], s[14:15], 0, v[148:149]
	s_add_i32 m0, s25, 0xe000
	s_nop 0
	global_load_lds_dwordx4 v[172:173], off
	s_waitcnt lgkmcnt(8)
	s_barrier
	s_waitcnt lgkmcnt(0)
	s_setprio 1
	s_waitcnt lgkmcnt(0)
	v_mfma_f32_16x16x32_bf16 v[142:145], v[98:101], v[152:155], v[142:145]
	v_mfma_f32_16x16x32_bf16 v[138:141], v[106:109], v[152:155], v[138:141]
	v_mfma_f32_16x16x32_bf16 v[134:137], v[98:101], v[176:179], v[134:137]
	v_mfma_f32_16x16x32_bf16 v[122:125], v[106:109], v[176:179], v[122:125]
	v_mfma_f32_16x16x32_bf16 v[94:97], v[98:101], v[184:187], v[94:97]
	v_mfma_f32_16x16x32_bf16 v[90:93], v[106:109], v[184:187], v[90:93]
	v_mfma_f32_16x16x32_bf16 v[86:89], v[98:101], v[192:195], v[86:89]
	v_mfma_f32_16x16x32_bf16 v[74:77], v[106:109], v[192:195], v[74:77]
	v_mfma_f32_16x16x32_bf16 v[142:145], v[102:105], v[156:159], v[142:145]
	v_mfma_f32_16x16x32_bf16 v[138:141], v[110:113], v[156:159], v[138:141]
	v_mfma_f32_16x16x32_bf16 v[134:137], v[102:105], v[180:183], v[134:137]
	v_mfma_f32_16x16x32_bf16 v[122:125], v[110:113], v[180:183], v[122:125]
	v_mfma_f32_16x16x32_bf16 v[94:97], v[102:105], v[188:191], v[94:97]
	v_mfma_f32_16x16x32_bf16 v[90:93], v[110:113], v[188:191], v[90:93]
	v_mfma_f32_16x16x32_bf16 v[86:89], v[102:105], v[196:199], v[86:89]
	v_mfma_f32_16x16x32_bf16 v[74:77], v[110:113], v[196:199], v[74:77]
	s_setprio 0
	s_barrier
	s_add_i32 s45, 0, 0x14000
	s_add_i32 s14, s44, s23
	v_add_u32_e32 v169, s45, v160
	v_lshl_add_u64 v[172:173], s[18:19], 0, v[0:1]
	s_mov_b32 m0, s14
	ds_read_b128 v[230:233], v169
	ds_read_b128 v[234:237], v169 offset:1024
	ds_read_b128 v[238:241], v169 offset:2048
	ds_read_b128 v[242:245], v169 offset:3072
	global_load_lds_dwordx4 v[172:173], off
	v_lshl_add_u64 v[174:175], s[18:19], 0, v[146:147]
	s_add_i32 m0, s14, 0x2000
	s_nop 0
	global_load_lds_dwordx4 v[174:175], off
	s_barrier
	s_waitcnt lgkmcnt(0)
	s_setprio 1
	s_waitcnt lgkmcnt(0)
	v_mfma_f32_16x16x32_bf16 v[130:133], v[230:233], v[152:155], v[130:133]
	v_mfma_f32_16x16x32_bf16 v[126:129], v[238:241], v[152:155], v[126:129]
	v_mfma_f32_16x16x32_bf16 v[118:121], v[230:233], v[176:179], v[118:121]
	v_mfma_f32_16x16x32_bf16 v[114:117], v[238:241], v[176:179], v[114:117]
	v_mfma_f32_16x16x32_bf16 v[82:85], v[230:233], v[184:187], v[82:85]
	v_mfma_f32_16x16x32_bf16 v[78:81], v[238:241], v[184:187], v[78:81]
	v_mfma_f32_16x16x32_bf16 v[70:73], v[230:233], v[192:195], v[70:73]
	v_mfma_f32_16x16x32_bf16 v[66:69], v[238:241], v[192:195], v[66:69]
	v_mfma_f32_16x16x32_bf16 v[130:133], v[234:237], v[156:159], v[130:133]
	v_mfma_f32_16x16x32_bf16 v[126:129], v[242:245], v[156:159], v[126:129]
	v_mfma_f32_16x16x32_bf16 v[118:121], v[234:237], v[180:183], v[118:121]
	v_mfma_f32_16x16x32_bf16 v[114:117], v[242:245], v[180:183], v[114:117]
	v_mfma_f32_16x16x32_bf16 v[82:85], v[234:237], v[188:191], v[82:85]
	v_mfma_f32_16x16x32_bf16 v[78:81], v[242:245], v[188:191], v[78:81]
	v_mfma_f32_16x16x32_bf16 v[70:73], v[234:237], v[196:199], v[70:73]
	v_mfma_f32_16x16x32_bf16 v[66:69], v[242:245], v[196:199], v[66:69]
	s_setprio 0
	s_mov_b32 m0, s25
	v_lshl_add_u64 v[200:201], s[20:21], 0, v[0:1]
	s_barrier
	s_cmp_lg_u32 s99, 0
	s_cbranch_scc1 .Lfd_skipr3
	ds_read_b128 v[152:155], v161 offset:16384
	ds_read_b128 v[156:159], v161 offset:17408
	ds_read_b128 v[176:179], v161 offset:18432
	ds_read_b128 v[180:183], v161 offset:19456
	ds_read_b128 v[184:187], v161 offset:20480
	ds_read_b128 v[188:191], v161 offset:21504
	ds_read_b128 v[192:195], v161 offset:22528
	ds_read_b128 v[196:199], v161 offset:23552
.Lfd_skipr3:
	global_load_lds_dwordx4 v[200:201], off
	v_lshl_add_u64 v[210:211], s[20:21], 0, v[146:147]
	s_mov_b32 m0, s26
	s_nop 0
	global_load_lds_dwordx4 v[210:211], off
	s_barrier
	s_waitcnt lgkmcnt(0)
	s_setprio 1
	s_waitcnt lgkmcnt(0)
	s_cmp_lg_u32 s99, 0
	s_cbranch_scc1 .Lfd_skip3
	v_mfma_f32_16x16x32_bf16 v[62:65], v[98:101], v[152:155], v[62:65]
	v_mfma_f32_16x16x32_bf16 v[58:61], v[106:109], v[152:155], v[58:61]
	v_mfma_f32_16x16x32_bf16 v[54:57], v[98:101], v[176:179], v[54:57]
	v_mfma_f32_16x16x32_bf16 v[42:45], v[106:109], v[176:179], v[42:45]
	v_mfma_f32_16x16x32_bf16 v[30:33], v[98:101], v[184:187], v[30:33]
	v_mfma_f32_16x16x32_bf16 v[26:29], v[106:109], v[184:187], v[26:29]
	v_mfma_f32_16x16x32_bf16 v[22:25], v[98:101], v[192:195], v[22:25]
	v_mfma_f32_16x16x32_bf16 v[18:21], v[106:109], v[192:195], v[18:21]
	v_mfma_f32_16x16x32_bf16 v[62:65], v[102:105], v[156:159], v[62:65]
	v_mfma_f32_16x16x32_bf16 v[58:61], v[110:113], v[156:159], v[58:61]
	v_mfma_f32_16x16x32_bf16 v[54:57], v[102:105], v[180:183], v[54:57]
	v_mfma_f32_16x16x32_bf16 v[42:45], v[110:113], v[180:183], v[42:45]
	v_mfma_f32_16x16x32_bf16 v[30:33], v[102:105], v[188:191], v[30:33]
	v_mfma_f32_16x16x32_bf16 v[26:29], v[110:113], v[188:191], v[26:29]
	v_mfma_f32_16x16x32_bf16 v[22:25], v[102:105], v[196:199], v[22:25]
	v_mfma_f32_16x16x32_bf16 v[18:21], v[110:113], v[196:199], v[18:21]

.Lfd_skip4:
	s_setprio 0
	s_add_i32 s44, 0, 0x18000
	v_add_u32_e32 v110, s44, v160
	s_barrier
	ds_read_b128 v[98:101], v110
	ds_read_b128 v[102:105], v110 offset:1024
	ds_read_b128 v[106:109], v110 offset:2048
	ds_read_b128 v[110:113], v110 offset:3072
	s_add_u32 s14, s20, 0xb0000
	s_addc_u32 s15, s21, 0
	s_mov_b32 m0, s27
	v_lshl_add_u64 v[230:231], s[14:15], 0, v[0:1]
	ds_read_b128 v[152:155], v161 offset:32768
	ds_read_b128 v[156:159], v161 offset:33792
	ds_read_b128 v[176:179], v161 offset:34816
	ds_read_b128 v[180:183], v161 offset:35840
	ds_read_b128 v[184:187], v161 offset:36864
	ds_read_b128 v[188:191], v161 offset:37888
	ds_read_b128 v[192:195], v161 offset:38912
	ds_read_b128 v[196:199], v161 offset:39936
	global_load_lds_dwordx4 v[230:231], off
	v_lshl_add_u64 v[230:231], s[14:15], 0, v[146:147]
	s_mov_b32 m0, s28
	s_nop 0
	global_load_lds_dwordx4 v[230:231], off
	s_waitcnt lgkmcnt(8)
	s_barrier
	s_waitcnt lgkmcnt(0)
	s_setprio 1
	s_waitcnt lgkmcnt(0)
	v_mfma_f32_16x16x32_bf16 v[142:145], v[98:101], v[152:155], v[142:145]
	v_mfma_f32_16x16x32_bf16 v[138:141], v[106:109], v[152:155], v[138:141]
	v_mfma_f32_16x16x32_bf16 v[134:137], v[98:101], v[176:179], v[134:137]
	v_mfma_f32_16x16x32_bf16 v[122:125], v[106:109], v[176:179], v[122:125]
	v_mfma_f32_16x16x32_bf16 v[94:97], v[98:101], v[184:187], v[94:97]
	v_mfma_f32_16x16x32_bf16 v[90:93], v[106:109], v[184:187], v[90:93]
	v_mfma_f32_16x16x32_bf16 v[86:89], v[98:101], v[192:195], v[86:89]
	v_mfma_f32_16x16x32_bf16 v[74:77], v[106:109], v[192:195], v[74:77]
	v_mfma_f32_16x16x32_bf16 v[142:145], v[102:105], v[156:159], v[142:145]
	v_mfma_f32_16x16x32_bf16 v[138:141], v[110:113], v[156:159], v[138:141]
	v_mfma_f32_16x16x32_bf16 v[134:137], v[102:105], v[180:183], v[134:137]
	v_mfma_f32_16x16x32_bf16 v[122:125], v[110:113], v[180:183], v[122:125]
	v_mfma_f32_16x16x32_bf16 v[94:97], v[102:105], v[188:191], v[94:97]
	v_mfma_f32_16x16x32_bf16 v[90:93], v[110:113], v[188:191], v[90:93]
	v_mfma_f32_16x16x32_bf16 v[86:89], v[102:105], v[196:199], v[86:89]
	v_mfma_f32_16x16x32_bf16 v[74:77], v[110:113], v[196:199], v[74:77]
	s_setprio 0
	s_barrier
	s_add_i32 s20, 0, 0x1c000
	s_add_i32 s14, s44, s23
	v_add_u32_e32 v169, s20, v160
	v_lshl_add_u64 v[172:173], v[172:173], 0, s[92:93]
	s_mov_b32 m0, s14
	ds_read_b128 v[230:233], v169
	ds_read_b128 v[234:237], v169 offset:1024
	ds_read_b128 v[238:241], v169 offset:2048
	ds_read_b128 v[242:245], v169 offset:3072
	global_load_lds_dwordx4 v[172:173], off
	v_lshl_add_u64 v[172:173], v[174:175], 0, s[92:93]
	s_add_i32 m0, s14, 0x2000
	s_nop 0
	global_load_lds_dwordx4 v[172:173], off
	s_barrier
	s_waitcnt lgkmcnt(0)
	s_setprio 1
	s_waitcnt lgkmcnt(0)
	v_mfma_f32_16x16x32_bf16 v[130:133], v[230:233], v[152:155], v[130:133]
	v_mfma_f32_16x16x32_bf16 v[126:129], v[238:241], v[152:155], v[126:129]
	v_mfma_f32_16x16x32_bf16 v[118:121], v[230:233], v[176:179], v[118:121]
	v_mfma_f32_16x16x32_bf16 v[114:117], v[238:241], v[176:179], v[114:117]
	v_mfma_f32_16x16x32_bf16 v[82:85], v[230:233], v[184:187], v[82:85]
	v_mfma_f32_16x16x32_bf16 v[78:81], v[238:241], v[184:187], v[78:81]
	v_mfma_f32_16x16x32_bf16 v[70:73], v[230:233], v[192:195], v[70:73]
	v_mfma_f32_16x16x32_bf16 v[66:69], v[238:241], v[192:195], v[66:69]
	v_mfma_f32_16x16x32_bf16 v[130:133], v[234:237], v[156:159], v[130:133]
	v_mfma_f32_16x16x32_bf16 v[126:129], v[242:245], v[156:159], v[126:129]
	v_mfma_f32_16x16x32_bf16 v[118:121], v[234:237], v[180:183], v[118:121]
	v_mfma_f32_16x16x32_bf16 v[114:117], v[242:245], v[180:183], v[114:117]
	v_mfma_f32_16x16x32_bf16 v[82:85], v[234:237], v[188:191], v[82:85]
	v_mfma_f32_16x16x32_bf16 v[78:81], v[242:245], v[188:191], v[78:81]
	v_mfma_f32_16x16x32_bf16 v[70:73], v[234:237], v[196:199], v[70:73]
	v_mfma_f32_16x16x32_bf16 v[66:69], v[242:245], v[196:199], v[66:69]
	s_setprio 0
	s_mov_b32 m0, s31
	v_lshl_add_u64 v[172:173], v[200:201], 0, s[92:93]
	s_barrier
	s_cmp_lg_u32 s99, 0
	s_cbranch_scc1 .Lfd_skipr7
	ds_read_b128 v[152:155], v161 offset:49152
	ds_read_b128 v[156:159], v161 offset:50176
	ds_read_b128 v[176:179], v161 offset:51200
	ds_read_b128 v[180:183], v161 offset:52224
	ds_read_b128 v[184:187], v161 offset:53248
	ds_read_b128 v[188:191], v161 offset:54272
	ds_read_b128 v[192:195], v161 offset:55296
	ds_read_b128 v[196:199], v161 offset:56320
.Lfd_skipr7:
	global_load_lds_dwordx4 v[172:173], off
	v_lshl_add_u64 v[172:173], v[210:211], 0, s[92:93]
	s_mov_b32 m0, s34
	s_nop 0
	global_load_lds_dwordx4 v[172:173], off
	s_barrier
	s_waitcnt lgkmcnt(0)
	s_setprio 1
	s_waitcnt lgkmcnt(0)
	s_cmp_lg_u32 s99, 0
	s_cbranch_scc1 .Lfd_skip7
	v_mfma_f32_16x16x32_bf16 v[62:65], v[98:101], v[152:155], v[62:65]
	v_mfma_f32_16x16x32_bf16 v[58:61], v[106:109], v[152:155], v[58:61]
	v_mfma_f32_16x16x32_bf16 v[54:57], v[98:101], v[176:179], v[54:57]
	v_mfma_f32_16x16x32_bf16 v[42:45], v[106:109], v[176:179], v[42:45]
	v_mfma_f32_16x16x32_bf16 v[30:33], v[98:101], v[184:187], v[30:33]
	v_mfma_f32_16x16x32_bf16 v[26:29], v[106:109], v[184:187], v[26:29]
	v_mfma_f32_16x16x32_bf16 v[22:25], v[98:101], v[192:195], v[22:25]
	v_mfma_f32_16x16x32_bf16 v[18:21], v[106:109], v[192:195], v[18:21]
	v_mfma_f32_16x16x32_bf16 v[62:65], v[102:105], v[156:159], v[62:65]
	v_mfma_f32_16x16x32_bf16 v[58:61], v[110:113], v[156:159], v[58:61]
	v_mfma_f32_16x16x32_bf16 v[54:57], v[102:105], v[180:183], v[54:57]
	v_mfma_f32_16x16x32_bf16 v[42:45], v[110:113], v[180:183], v[42:45]
	v_mfma_f32_16x16x32_bf16 v[30:33], v[102:105], v[188:191], v[30:33]
	v_mfma_f32_16x16x32_bf16 v[26:29], v[110:113], v[188:191], v[26:29]
	v_mfma_f32_16x16x32_bf16 v[22:25], v[102:105], v[196:199], v[22:25]
	v_mfma_f32_16x16x32_bf16 v[18:21], v[110:113], v[196:199], v[18:21]
